# P5 attention step: PV V-fragment double buffering + K/V LDS staging writes at step top + early K-fragment reads (each confirmed with a 4x-P5 amplification run); plus g2 rewrite, P9 epilogue wait fix,
# baseline (speedup 1.0000x reference)
.LBB0_1802:
	s_add_i32 s2, s83, 3
	s_add_i32 s94, s83, 2
	s_min_i32 s2, s2, s97
	s_min_i32 s3, s94, s97
	s_mul_i32 s2, s2, 0xf8000
	s_mul_i32 s3, s3, 0xf8000
	v_add_u32_e32 v2, s2, v216
	s_waitcnt vmcnt(0)
	ds_write_b128 v231, v[146:149]
	ds_write_b128 v231, v[150:153] offset:27648
	v_add_u32_e32 v8, s3, v216
	global_load_dwordx4 v[4:7], v2, s[84:85]
	s_nop 0
	global_load_dwordx4 v[8:11], v8, s[84:85] offset:128
	ds_read_b128 v[22:25], v233 offset:9248
	ds_read_b128 v[26:29], v233 offset:13824
	ds_read_b128 v[30:33], v233 offset:13856
	s_add_i32 s2, s83, 1
	s_lshl_b32 s95, 1, s2
	v_and_b32_e32 v12, s95, v155
	v_cmp_ne_u32_e64 s[72:73], 0, v12
	s_andn2_b64 vcc, exec, s[0:1]
	s_mov_b64 s[0:1], -1
	v_cndmask_b32_e64 v130, v232, v20, s[72:73]
	v_mov_b32_e32 v131, v130
	v_mov_b32_e32 v132, v130
	v_mov_b32_e32 v133, v130
	v_mov_b32_e32 v134, v130
	v_mov_b32_e32 v135, v130
	v_mov_b32_e32 v136, v130
	v_mov_b32_e32 v137, v130
	v_mov_b32_e32 v138, v130
	v_mov_b32_e32 v139, v130
	v_mov_b32_e32 v140, v130
	v_mov_b32_e32 v141, v130
	v_mov_b32_e32 v142, v130
	v_mov_b32_e32 v143, v130
	v_mov_b32_e32 v144, v130
	v_mov_b32_e32 v145, v130
	s_cbranch_vccz .LBB0_1804
	ds_read_b128 v[12:15], v233 offset:9216
	s_mov_b64 s[0:1], 0
	s_waitcnt lgkmcnt(0)
	v_mfma_f32_32x32x16_bf16 v[66:81], v[12:15], v[206:209], v[130:145]
	ds_read_b128 v[12:15], v233 offset:13824
	s_waitcnt lgkmcnt(0)
	v_mfma_f32_32x32x16_bf16 v[82:97], v[12:15], v[206:209], v[130:145]
	ds_read_b128 v[12:15], v233 offset:9248
	s_waitcnt lgkmcnt(0)
	v_mfma_f32_32x32x16_bf16 v[66:81], v[12:15], v[202:205], v[66:81]
	ds_read_b128 v[12:15], v233 offset:13856
	s_waitcnt lgkmcnt(0)
	v_mfma_f32_32x32x16_bf16 v[82:97], v[12:15], v[202:205], v[82:97]
	ds_read_b128 v[12:15], v233 offset:9280
	s_waitcnt lgkmcnt(0)
	v_mfma_f32_32x32x16_bf16 v[66:81], v[12:15], v[198:201], v[66:81]
	ds_read_b128 v[12:15], v233 offset:13888
	s_waitcnt lgkmcnt(0)
	v_mfma_f32_32x32x16_bf16 v[82:97], v[12:15], v[198:201], v[82:97]
	ds_read_b128 v[12:15], v233 offset:9312
	s_waitcnt lgkmcnt(0)
	v_mfma_f32_32x32x16_bf16 v[66:81], v[12:15], v[194:197], v[66:81]
	ds_read_b128 v[12:15], v233 offset:13920
	s_waitcnt lgkmcnt(0)
	v_mfma_f32_32x32x16_bf16 v[82:97], v[12:15], v[194:197], v[82:97]

.LBB0_1807:
	s_cmp_lg_u64 s[72:73], 0
	s_waitcnt lgkmcnt(0)
	s_barrier
	s_cselect_b64 s[0:1], -1, 0
	s_cmp_eq_u64 s[72:73], 0
	v_lshl_add_u64 v[12:13], s[84:85], 0, v[2:3]
	s_cselect_b64 s[86:87], -1, 0
	s_cmp_gt_i32 s94, s97
	s_cbranch_scc1 .LBB0_1814
	s_waitcnt vmcnt(0)
	ds_write_b128 v231, v[4:7] offset:9216
	ds_write_b128 v231, v[8:11] offset:18432
	s_add_i32 s0, s83, 4
	s_min_i32 s0, s0, s97
	s_mul_i32 s0, s0, 0xf8000
	v_add_u32_e32 v2, s0, v216
	global_load_dwordx4 v[146:149], v2, s[84:85]
	global_load_dwordx4 v[150:153], v[12:13], off offset:128
	ds_read_b128 v[22:25], v233 offset:32
	ds_read_b128 v[26:29], v233 offset:4608
	ds_read_b128 v[30:33], v233 offset:4640
	s_and_b32 s72, s94, 30
	s_cmp_eq_u32 s72, 0
	s_cselect_b64 vcc, -1, 0
	s_cmp_eq_u32 s83, 30
	s_cselect_b64 s[0:1], -1, 0
	s_cmp_eq_u32 s83, 62
	s_cselect_b64 s[2:3], -1, 0
	v_cndmask_b32_e64 v2, v213, v212, s[2:3]
	v_cndmask_b32_e64 v2, v2, v211, s[0:1]
	v_cndmask_b32_e32 v155, v155, v2, vcc
	v_lshrrev_b32_e32 v2, s72, v155
	v_and_b32_e32 v2, 1, v2
	v_cmp_eq_u32_e32 vcc, 1, v2
	v_bfe_u32 v12, v155, s72, 1
	v_cmp_ne_u32_e64 s[72:73], 0, v12
	v_cndmask_b32_e32 v130, v232, v20, vcc
	v_mov_b32_e32 v131, v130
	v_mov_b32_e32 v132, v130
	v_mov_b32_e32 v133, v130
	v_mov_b32_e32 v134, v130
	v_mov_b32_e32 v135, v130
	v_mov_b32_e32 v136, v130
	v_mov_b32_e32 v137, v130
	v_mov_b32_e32 v138, v130
	v_mov_b32_e32 v139, v130
	v_mov_b32_e32 v140, v130
	v_mov_b32_e32 v141, v130
	v_mov_b32_e32 v142, v130
	v_mov_b32_e32 v143, v130
	v_mov_b32_e32 v144, v130
	v_mov_b32_e32 v145, v130
	s_mov_b64 s[0:1], -1
	s_and_b64 vcc, exec, s[86:87]
	s_cbranch_vccz .LBB0_1810
	ds_read_b128 v[12:15], v233
	s_mov_b64 s[0:1], 0
	s_waitcnt lgkmcnt(0)
	v_mfma_f32_32x32x16_bf16 v[98:113], v[12:15], v[206:209], v[130:145]
	ds_read_b128 v[12:15], v233 offset:4608
	s_waitcnt lgkmcnt(0)
	v_mfma_f32_32x32x16_bf16 v[114:129], v[12:15], v[206:209], v[130:145]
	ds_read_b128 v[12:15], v233 offset:32
	s_waitcnt lgkmcnt(0)
	v_mfma_f32_32x32x16_bf16 v[98:113], v[12:15], v[202:205], v[98:113]
	ds_read_b128 v[12:15], v233 offset:4640
	s_waitcnt lgkmcnt(0)
	v_mfma_f32_32x32x16_bf16 v[114:129], v[12:15], v[202:205], v[114:129]
	ds_read_b128 v[12:15], v233 offset:64
	s_waitcnt lgkmcnt(0)
	v_mfma_f32_32x32x16_bf16 v[98:113], v[12:15], v[198:201], v[98:113]
	ds_read_b128 v[12:15], v233 offset:4672
	s_waitcnt lgkmcnt(0)
	v_mfma_f32_32x32x16_bf16 v[114:129], v[12:15], v[198:201], v[114:129]
	ds_read_b128 v[12:15], v233 offset:96
	s_waitcnt lgkmcnt(0)
	v_mfma_f32_32x32x16_bf16 v[98:113], v[12:15], v[194:197], v[98:113]
	ds_read_b128 v[12:15], v233 offset:4704
	s_waitcnt lgkmcnt(0)
	v_mfma_f32_32x32x16_bf16 v[114:129], v[12:15], v[194:197], v[114:129]
